# k11
# baseline (speedup 1.0000x reference)
; __device__ __forceinline__ void finishSM(f32x16& p0, f32x16& p1, float alpha, float& l_reg, bf16x8& pa0, bf16x8& pa1, bf16x8& pa2, bf16x8& pa3) {
;   for (int r = 0; r < 16; ++r) p1[r] = __builtin_amdgcn_exp2f(p1[r]);
;   float ps = 0; for (int r = 0; r < 16; ++r) ps += p0[r]; for (int r = 0; r < 16; ++r) ps += p1[r];
;   { auto rr = __builtin_amdgcn_permlane32_swap(__float_as_uint(ps), __float_as_uint(ps), false, false);
;     ps = __uint_as_float(rr[0]) + __uint_as_float(rr[1]); }
;   l_reg = l_reg * alpha + ps;
;     ...
;   PK4(p0, 0, pa0); PK4(p0, 8, pa1); PK4(p1, 0, pa2); PK4(p1, 8, pa3);
;     ...
; }
; __device__ __forceinline__ void qkt(f32x16& p0, f32x16& p1, const u16* Ks, const bf16x8* qr, int r32, int hi) {
;   p0 = f32x16{}; p1 = f32x16{};
;   for (int d0 = 0; d0 < 8; ++d0) { int cb = (d0 * 16 + hi * 8) * 2;
;     bf16x8 b0 = *reinterpret_cast<const bf16x8*>((const char*)Ks + KSWZ(r32, cb));
;     bf16x8 b1 = *reinterpret_cast<const bf16x8*>((const char*)Ks + KSWZ(32 + r32, cb));
;     p0 = __builtin_amdgcn_mfma_f32_32x32x16_bf16(b0, qr[d0], p0, 0, 0, 0);
;     p1 = __builtin_amdgcn_mfma_f32_32x32x16_bf16(b1, qr[d0], p1, 0, 0, 0); }
; }
; __device__ __forceinline__ int v_st(int k, int c) { const int kk = (k & ~0xC) | ((k & 4) << 1) | ((k & 8) >> 1); return ((kk >> 3) * 4 + (c >> 5)) * 512 + ((kk & 7) * 32 + (c & 31)) * 2; }
; __device__ __forceinline__ int v_rd_base(int lane) { return ((lane & 3) << 3) | (((lane >> 2) & 3) << 6) | (((lane >> 4) & 1) << 5) | (((lane >> 5) & 1) << 8); }
; template <int OFF> __device__ __forceinline__ s16x4 tr_read(int vb) {
;   s16x4 r; asm volatile("ds_read_b64_tr_b16 %0, %1 offset:%2" : "=&v"(r) : "v"(vb), "i"(OFF) : "memory"); return r;
; }
; template <int D0> __device__ __forceinline__ void pv_one(f32x16& od, int vb, bf16x8 pa0, bf16x8 pa1, bf16x8 pa2, bf16x8 pa3) {
;   const s16x4 l0 = tr_read<v_rd_off(D0, 0, 0)>(vb), h0 = tr_read<v_rd_off(D0, 0, 1)>(vb), l1 = tr_read<v_rd_off(D0, 1, 0)>(vb), h1 = tr_read<v_rd_off(D0, 1, 1)>(vb);
;   const s16x4 l2 = tr_read<v_rd_off(D0, 2, 0)>(vb), h2 = tr_read<v_rd_off(D0, 2, 1)>(vb), l3 = tr_read<v_rd_off(D0, 3, 0)>(vb), h3 = tr_read<v_rd_off(D0, 3, 1)>(vb);
;   asm volatile("s_waitcnt lgkmcnt(0)" ::: "memory"); SBAR();
;     ...
;   od = __builtin_amdgcn_mfma_f32_32x32x16_bf16(pa0, PK(l0, h0), od, 0, 0, 0);
;   od = __builtin_amdgcn_mfma_f32_32x32x16_bf16(pa1, PK(l1, h1), od, 0, 0, 0);
.LBB0_858:
	ds_read_b128 v[64:67], v201 offset:49152
	ds_read_b128 v[68:71], v201 offset:57344
	ds_read_b128 v[218:221], v204 offset:49152
	ds_read_b128 v[222:225], v204 offset:57344
	v_add_f32_e32 v160, 0, v175
	v_add_f32_e32 v160, v216, v160
	s_waitcnt lgkmcnt(3)
	v_mfma_f32_32x32x16_bf16 v[80:95], v[64:67], v[96:99], 0
	v_add_f32_e32 v160, v161, v160
	v_add_f32_e32 v160, v213, v160
	v_add_f32_e32 v160, v162, v160
	v_add_f32_e32 v160, v174, v160
	v_add_f32_e32 v160, v163, v160
	v_add_f32_e32 v160, v173, v160
	v_add_f32_e32 v160, v170, v160
	s_waitcnt lgkmcnt(2)
	v_mfma_f32_32x32x16_bf16 v[64:79], v[68:71], v[96:99], 0
	v_add_f32_e32 v160, v172, v160
	v_add_f32_e32 v160, v169, v160
	v_add_f32_e32 v160, v171, v160
	v_exp_f32_e32 v156, v156
	v_add_f32_e32 v160, v166, v160
	v_exp_f32_e32 v157, v157
	v_add_f32_e32 v160, v168, v160
	s_waitcnt lgkmcnt(1)
	v_mfma_f32_32x32x16_bf16 v[80:95], v[218:221], v[100:103], v[80:95]
	v_exp_f32_e32 v154, v154
	v_add_f32_e32 v160, v165, v160
	v_exp_f32_e32 v155, v155
	v_add_f32_e32 v160, v167, v160
	v_exp_f32_e32 v148, v148
	v_add_f32_e32 v160, v156, v160
	v_exp_f32_e32 v149, v149
	s_waitcnt lgkmcnt(0)
	v_mfma_f32_32x32x16_bf16 v[64:79], v[222:225], v[100:103], v[64:79]
	ds_read_b128 v[218:221], v206 offset:49152
	ds_read_b128 v[222:225], v206 offset:57344
	v_add_f32_e32 v160, v157, v160
	v_exp_f32_e32 v146, v146
	v_add_f32_e32 v160, v154, v160
	v_exp_f32_e32 v147, v147
	v_add_f32_e32 v160, v155, v160
	v_exp_f32_e32 v144, v144
	s_waitcnt lgkmcnt(1)
	v_mfma_f32_32x32x16_bf16 v[80:95], v[218:221], v[104:107], v[80:95]
	v_add_f32_e32 v160, v148, v160
	v_exp_f32_e32 v145, v145
	v_add_f32_e32 v160, v149, v160
	v_exp_f32_e32 v158, v158
	v_add_f32_e32 v160, v146, v160
	v_exp_f32_e32 v159, v159
	v_add_f32_e32 v160, v147, v160
	s_waitcnt lgkmcnt(0)
	v_mfma_f32_32x32x16_bf16 v[64:79], v[222:225], v[104:107], v[64:79]
	ds_read_b128 v[218:221], v202 offset:49152
	ds_read_b128 v[222:225], v202 offset:57344
	v_exp_f32_e32 v152, v152
	v_add_f32_e32 v160, v144, v160
	v_exp_f32_e32 v153, v153
	v_add_f32_e32 v160, v145, v160
	v_exp_f32_e32 v150, v150
	v_add_f32_e32 v160, v158, v160
	s_waitcnt lgkmcnt(1)
	v_mfma_f32_32x32x16_bf16 v[80:95], v[218:221], v[108:111], v[80:95]
	v_exp_f32_e32 v151, v151
	v_add_f32_e32 v160, v159, v160
	v_add_f32_e32 v160, v152, v160
	v_add_f32_e32 v160, v153, v160
	v_add_f32_e32 v160, v150, v160
	v_add_f32_e32 v210, v151, v160
	v_mov_b32_e32 v211, v210
	s_waitcnt lgkmcnt(0)
	v_mfma_f32_32x32x16_bf16 v[64:79], v[222:225], v[108:111], v[64:79]
	ds_read_b128 v[218:221], v203 offset:49152
	ds_read_b128 v[222:225], v203 offset:57344
	v_permlane32_swap_b32_e32 v210, v211
	s_waitcnt lgkmcnt(1)
	v_mfma_f32_32x32x16_bf16 v[80:95], v[218:221], v[112:115], v[80:95]
	s_waitcnt lgkmcnt(0)
	v_mfma_f32_32x32x16_bf16 v[64:79], v[222:225], v[112:115], v[64:79]
	ds_read_b128 v[218:221], v205 offset:49152
	ds_read_b128 v[222:225], v205 offset:57344
	s_waitcnt lgkmcnt(1)
	v_mfma_f32_32x32x16_bf16 v[80:95], v[218:221], v[116:119], v[80:95]
	s_waitcnt lgkmcnt(0)
	v_mfma_f32_32x32x16_bf16 v[64:79], v[222:225], v[116:119], v[64:79]
	ds_read_b128 v[218:221], v207 offset:49152
	ds_read_b128 v[222:225], v207 offset:57344
	s_waitcnt lgkmcnt(1)
	v_mfma_f32_32x32x16_bf16 v[80:95], v[218:221], v[120:123], v[80:95]
	s_waitcnt lgkmcnt(0)
	v_mfma_f32_32x32x16_bf16 v[64:79], v[222:225], v[120:123], v[64:79]
	ds_read_b128 v[218:221], v208 offset:49152
	ds_read_b128 v[222:225], v208 offset:57344
	v_cvt_pk_bf16_f32 v160, v175, v216
	v_cvt_pk_bf16_f32 v161, v161, v213
	v_cvt_pk_bf16_f32 v162, v162, v174
	v_cvt_pk_bf16_f32 v163, v163, v173
	v_cvt_pk_bf16_f32 v170, v170, v172
	v_cvt_pk_bf16_f32 v171, v169, v171
	s_waitcnt lgkmcnt(1)
	v_mfma_f32_32x32x16_bf16 v[80:95], v[218:221], v[124:127], v[80:95]
	v_cvt_pk_bf16_f32 v172, v166, v168
	v_cvt_pk_bf16_f32 v173, v165, v167
	v_cvt_pk_bf16_f32 v166, v156, v157
	v_cvt_pk_bf16_f32 v167, v154, v155
	v_cvt_pk_bf16_f32 v168, v148, v149
	v_cvt_pk_bf16_f32 v169, v146, v147
	v_cvt_pk_bf16_f32 v212, v144, v145
	s_waitcnt lgkmcnt(0)
	v_mfma_f32_32x32x16_bf16 v[64:79], v[222:225], v[124:127], v[64:79]
	v_cvt_pk_bf16_f32 v213, v158, v159
	v_cvt_pk_bf16_f32 v214, v152, v153
	v_permlane32_swap_b32_e32 v160, v162
	v_cvt_pk_bf16_f32 v215, v150, v151
	v_permlane32_swap_b32_e32 v212, v214
	v_permlane32_swap_b32_e32 v161, v163
	v_permlane32_swap_b32_e32 v170, v172
	v_permlane32_swap_b32_e32 v171, v173
	v_permlane32_swap_b32_e32 v166, v168
	v_permlane32_swap_b32_e32 v167, v169
	v_permlane32_swap_b32_e32 v213, v215
	s_mov_b32 s1, 0xfffb8000
	v_add_co_u32_e32 v148, vcc, s1, v180
	s_mov_b32 s1, 0xfffd0000
	s_nop 0
	v_addc_co_u32_e32 v149, vcc, -1, v181, vcc
	v_add_co_u32_e32 v152, vcc, s1, v180
	s_nop 1
	v_addc_co_u32_e32 v153, vcc, -1, v181, vcc
	global_load_dwordx4 v[144:147], v[148:149], off
	s_nop 0
	global_load_dwordx4 v[148:151], v[148:149], off offset:-512
	s_nop 0
	global_load_dwordx4 v[156:159], v[152:153], off
	s_nop 0
	global_load_dwordx4 v[152:155], v[152:153], off offset:-512
	ds_read_b64_tr_b16 v[216:217], v196 offset:0
	ds_read_b64_tr_b16 v[218:219], v196 offset:0x800
	ds_read_b64_tr_b16 v[220:221], v196 offset:0x1000
	ds_read_b64_tr_b16 v[222:223], v196 offset:0x1800
	ds_read_b64_tr_b16 v[224:225], v196 offset:0x2000
	ds_read_b64_tr_b16 v[226:227], v196 offset:0x2800
	ds_read_b64_tr_b16 v[228:229], v196 offset:0x3000
	ds_read_b64_tr_b16 v[230:231], v196 offset:0x3800
	s_waitcnt lgkmcnt(6)
	s_nop 0
	v_mfma_f32_32x32x16_bf16 v[0:15], v[160:163], v[216:219], v[0:15]
	ds_read_b64_tr_b16 v[216:217], v196 offset:0x200
	ds_read_b64_tr_b16 v[218:219], v196 offset:0xa00
	s_waitcnt lgkmcnt(6)
; __device__ __forceinline__ void partialSM(f32x16& p0, f32x16& p1, float& m_reg, float& mn, float& alpha) {
;   constexpr float C = ASCALE * 1.4426950408889634f;
;   float pmax = p0[0]; for (int r = 1; r < 16; ++r) pmax = fmaxf(pmax, p0[r]); for (int r = 0; r < 16; ++r) pmax = fmaxf(pmax, p1[r]);
;   { auto rr = __builtin_amdgcn_permlane32_swap(__float_as_uint(pmax), __float_as_uint(pmax), false, false);
;     pmax = fmaxf(__uint_as_float(rr[0]), __uint_as_float(rr[1])); }
;   if (__builtin_expect(__all(pmax - m_reg <= ATHR / ASCALE), 1)) { mn = m_reg; alpha = 1.f; }
;   else { mn = fmaxf(m_reg, pmax); alpha = __builtin_amdgcn_exp2f((m_reg - mn) * C); m_reg = mn; }
;   float mnC = -mn * C;
;   for (int r = 0; r < 16; ++r) p0[r] = fmaf(p0[r], C, mnC); for (int r = 0; r < 16; ++r) p1[r] = fmaf(p1[r], C, mnC);
;   for (int r = 0; r < 16; ++r) p0[r] = __builtin_amdgcn_exp2f(p0[r]);
; }
; __device__ __forceinline__ void finishSM(f32x16& p0, f32x16& p1, float alpha, float& l_reg, bf16x8& pa0, bf16x8& pa1, bf16x8& pa2, bf16x8& pa3) {
;   for (int r = 0; r < 16; ++r) p1[r] = __builtin_amdgcn_exp2f(p1[r]);
;   float ps = 0; for (int r = 0; r < 16; ++r) ps += p0[r]; for (int r = 0; r < 16; ++r) ps += p1[r];
;   { auto rr = __builtin_amdgcn_permlane32_swap(__float_as_uint(ps), __float_as_uint(ps), false, false);
;     ps = __uint_as_float(rr[0]) + __uint_as_float(rr[1]); }
;   l_reg = l_reg * alpha + ps;
;     ...
;   PK4(p0, 0, pa0); PK4(p0, 8, pa1); PK4(p1, 0, pa2); PK4(p1, 8, pa3);
;     ...
; }
; __device__ __forceinline__ void qkt(f32x16& p0, f32x16& p1, const u16* Ks, const bf16x8* qr, int r32, int hi) {
;   p0 = f32x16{}; p1 = f32x16{};
;   for (int d0 = 0; d0 < 8; ++d0) { int cb = (d0 * 16 + hi * 8) * 2;
;     bf16x8 b0 = *reinterpret_cast<const bf16x8*>((const char*)Ks + KSWZ(r32, cb));
;     bf16x8 b1 = *reinterpret_cast<const bf16x8*>((const char*)Ks + KSWZ(32 + r32, cb));
;     p0 = __builtin_amdgcn_mfma_f32_32x32x16_bf16(b0, qr[d0], p0, 0, 0, 0);
;     p1 = __builtin_amdgcn_mfma_f32_32x32x16_bf16(b1, qr[d0], p1, 0, 0, 0); }
; }
; __device__ __forceinline__ int v_st(int k, int c) { const int kk = (k & ~0xC) | ((k & 4) << 1) | ((k & 8) >> 1); return ((kk >> 3) * 4 + (c >> 5)) * 512 + ((kk & 7) * 32 + (c & 31)) * 2; }
	v_mfma_f32_32x32x16_bf16 v[0:15], v[170:173], v[220:223], v[0:15]
	ds_read_b64_tr_b16 v[220:221], v196 offset:0x1200
	ds_read_b64_tr_b16 v[222:223], v196 offset:0x1a00
	s_waitcnt lgkmcnt(6)
	v_mfma_f32_32x32x16_bf16 v[0:15], v[166:169], v[224:227], v[0:15]
	ds_read_b64_tr_b16 v[224:225], v196 offset:0x2200
	ds_read_b64_tr_b16 v[226:227], v196 offset:0x2a00
	s_waitcnt lgkmcnt(6)
	v_mfma_f32_32x32x16_bf16 v[0:15], v[212:215], v[228:231], v[0:15]
	ds_read_b64_tr_b16 v[228:229], v196 offset:0x3200
	ds_read_b64_tr_b16 v[230:231], v196 offset:0x3a00
	s_waitcnt lgkmcnt(6)
	v_mfma_f32_32x32x16_bf16 v[48:63], v[160:163], v[216:219], v[48:63]
	ds_read_b64_tr_b16 v[216:217], v196 offset:0x400
	ds_read_b64_tr_b16 v[218:219], v196 offset:0xc00
	s_waitcnt lgkmcnt(6)
	v_mfma_f32_32x32x16_bf16 v[48:63], v[170:173], v[220:223], v[48:63]
	ds_read_b64_tr_b16 v[220:221], v196 offset:0x1400
	ds_read_b64_tr_b16 v[222:223], v196 offset:0x1c00
	s_waitcnt lgkmcnt(6)
	v_mfma_f32_32x32x16_bf16 v[48:63], v[166:169], v[224:227], v[48:63]
	ds_read_b64_tr_b16 v[224:225], v196 offset:0x2400
	ds_read_b64_tr_b16 v[226:227], v196 offset:0x2c00
	s_waitcnt lgkmcnt(6)
	v_mfma_f32_32x32x16_bf16 v[48:63], v[212:215], v[228:231], v[48:63]
	ds_read_b64_tr_b16 v[228:229], v196 offset:0x3400
	ds_read_b64_tr_b16 v[230:231], v196 offset:0x3c00
	s_waitcnt lgkmcnt(6)
	v_mfma_f32_32x32x16_bf16 v[32:47], v[160:163], v[216:219], v[32:47]
	ds_read_b64_tr_b16 v[216:217], v196 offset:0x600
	ds_read_b64_tr_b16 v[218:219], v196 offset:0xe00
	s_waitcnt lgkmcnt(6)
	v_mfma_f32_32x32x16_bf16 v[32:47], v[170:173], v[220:223], v[32:47]
	ds_read_b64_tr_b16 v[220:221], v196 offset:0x1600
	ds_read_b64_tr_b16 v[222:223], v196 offset:0x1e00
	s_waitcnt lgkmcnt(6)
	v_mfma_f32_32x32x16_bf16 v[32:47], v[166:169], v[224:227], v[32:47]
	ds_read_b64_tr_b16 v[224:225], v196 offset:0x2600
	ds_read_b64_tr_b16 v[226:227], v196 offset:0x2e00
	s_waitcnt lgkmcnt(6)
	v_mfma_f32_32x32x16_bf16 v[32:47], v[212:215], v[228:231], v[32:47]
	ds_read_b64_tr_b16 v[228:229], v196 offset:0x3600
	ds_read_b64_tr_b16 v[230:231], v196 offset:0x3e00
	s_waitcnt lgkmcnt(6)
	v_mfma_f32_32x32x16_bf16 v[16:31], v[160:163], v[216:219], v[16:31]
	v_max_f32_e32 v160, v81, v81
	v_max_f32_e32 v161, v80, v80
	v_max_f32_e32 v160, v161, v160
	v_max3_f32 v160, v160, v82, v83
	v_max3_f32 v160, v160, v84, v85
	v_max3_f32 v160, v160, v86, v87
	v_max3_f32 v160, v160, v88, v89
	v_max3_f32 v160, v160, v90, v91
	v_max3_f32 v160, v160, v92, v93
	s_waitcnt lgkmcnt(4)
	v_mfma_f32_32x32x16_bf16 v[16:31], v[170:173], v[220:223], v[16:31]
	v_max3_f32 v160, v160, v94, v95
	v_max3_f32 v160, v160, v64, v65
	v_max3_f32 v160, v160, v66, v67
	v_max3_f32 v160, v160, v68, v69
	v_max3_f32 v160, v160, v70, v71
	v_max3_f32 v160, v160, v72, v73
	v_max3_f32 v160, v160, v74, v75
	v_max3_f32 v160, v160, v76, v77
	s_waitcnt lgkmcnt(2)
	v_mfma_f32_32x32x16_bf16 v[16:31], v[166:169], v[224:227], v[16:31]
	v_max3_f32 v160, v160, v78, v79
	v_mov_b32_e32 v161, v160
	s_nop 1
	v_permlane32_swap_b32_e32 v160, v161
	v_max_f32_e32 v161, v161, v161
	v_max_f32_e32 v160, v160, v160
	v_max_f32_e32 v160, v160, v161
	v_sub_f32_e32 v161, v160, v164
	v_cmp_ge_f32_e32 vcc, s56, v161
	v_max_f32_e32 v161, v164, v164
	v_max_f32_e32 v160, v161, v160
	s_waitcnt lgkmcnt(0)
	v_mfma_f32_32x32x16_bf16 v[16:31], v[212:215], v[228:231], v[16:31]
	v_sub_f32_e32 v161, v164, v160
	v_mul_f32_e32 v161, 0x3e0293ee, v161
	v_exp_f32_e32 v161, v161
	s_cmp_eq_u64 vcc, exec
	s_cselect_b64 s[10:11], -1, 0
	s_barrier
	s_waitcnt vmcnt(4)
	v_cndmask_b32_e64 v212, v161, 1.0, s[10:11]
	v_cmp_gt_f32_e32 vcc, 1.0, v212
	s_waitcnt vmcnt(4)
	ds_write_b128 v197, v[132:135]
	ds_write_b128 v198, v[140:143]
	ds_write_b128 v199, v[136:139] offset:32768
	ds_write_b128 v200, v[128:131] offset:32768
	s_cbranch_vccz .LBB0_862
	s_and_saveexec_b64 s[4:5], s[8:9]
	ds_write_b32 v193, v212 offset:128
	s_or_b64 exec, exec, s[4:5]
	s_waitcnt lgkmcnt(0)
	v_add_u32_e32 v161, v179, v176
	ds_read_b128 v[166:169], v161 offset:224
	ds_read_b128 v[170:173], v161 offset:192
	ds_read_b128 v[214:217], v161 offset:160
	ds_read_b128 v[218:221], v161 offset:128
	s_waitcnt lgkmcnt(3)
	v_pk_mul_f32 v[12:13], v[12:13], v[166:167]
	s_waitcnt lgkmcnt(2)
	v_pk_mul_f32 v[8:9], v[8:9], v[170:171]
	s_waitcnt lgkmcnt(1)
	v_pk_mul_f32 v[4:5], v[4:5], v[214:215]
	v_pk_mul_f32 v[14:15], v[14:15], v[168:169]
	v_pk_mul_f32 v[10:11], v[10:11], v[172:173]
	v_pk_mul_f32 v[6:7], v[6:7], v[216:217]
	s_waitcnt lgkmcnt(0)
	v_pk_mul_f32 v[2:3], v[2:3], v[220:221]
	v_pk_mul_f32 v[0:1], v[0:1], v[218:219]
	v_pk_mul_f32 v[60:61], v[60:61], v[166:167]
	v_pk_mul_f32 v[56:57], v[56:57], v[170:171]
	v_pk_mul_f32 v[52:53], v[52:53], v[214:215]
	v_pk_mul_f32 v[62:63], v[62:63], v[168:169]
	v_pk_mul_f32 v[58:59], v[58:59], v[172:173]
	v_pk_mul_f32 v[54:55], v[54:55], v[216:217]
	v_pk_mul_f32 v[50:51], v[50:51], v[220:221]
	v_pk_mul_f32 v[48:49], v[48:49], v[218:219]
	v_pk_mul_f32 v[44:45], v[44:45], v[166:167]
	v_pk_mul_f32 v[40:41], v[40:41], v[170:171]
	v_pk_mul_f32 v[36:37], v[36:37], v[214:215]
	v_pk_mul_f32 v[46:47], v[46:47], v[168:169]
	v_pk_mul_f32 v[42:43], v[42:43], v[172:173]
	v_pk_mul_f32 v[38:39], v[38:39], v[216:217]
	v_pk_mul_f32 v[34:35], v[34:35], v[220:221]
	v_pk_mul_f32 v[32:33], v[32:33], v[218:219]
	v_pk_mul_f32 v[28:29], v[28:29], v[166:167]
	v_pk_mul_f32 v[24:25], v[24:25], v[170:171]
	v_pk_mul_f32 v[20:21], v[20:21], v[214:215]
	v_pk_mul_f32 v[30:31], v[30:31], v[168:169]
	v_pk_mul_f32 v[26:27], v[26:27], v[172:173]
	v_pk_mul_f32 v[22:23], v[22:23], v[216:217]
	v_pk_mul_f32 v[18:19], v[18:19], v[220:221]
	v_pk_mul_f32 v[16:17], v[16:17], v[218:219]

; __device__ __forceinline__ void partialSM(f32x16& p0, f32x16& p1, float& m_reg, float& mn, float& alpha) {
;   constexpr float C = ASCALE * 1.4426950408889634f;
;   float pmax = p0[0]; for (int r = 1; r < 16; ++r) pmax = fmaxf(pmax, p0[r]); for (int r = 0; r < 16; ++r) pmax = fmaxf(pmax, p1[r]);
;   { auto rr = __builtin_amdgcn_permlane32_swap(__float_as_uint(pmax), __float_as_uint(pmax), false, false);
;     pmax = fmaxf(__uint_as_float(rr[0]), __uint_as_float(rr[1])); }
;   if (__builtin_expect(__all(pmax - m_reg <= ATHR / ASCALE), 1)) { mn = m_reg; alpha = 1.f; }
;   else { mn = fmaxf(m_reg, pmax); alpha = __builtin_amdgcn_exp2f((m_reg - mn) * C); m_reg = mn; }
;   float mnC = -mn * C;
;   for (int r = 0; r < 16; ++r) p0[r] = fmaf(p0[r], C, mnC); for (int r = 0; r < 16; ++r) p1[r] = fmaf(p1[r], C, mnC);
;   for (int r = 0; r < 16; ++r) p0[r] = __builtin_amdgcn_exp2f(p0[r]);
; }
; __device__ __forceinline__ void finishSM(f32x16& p0, f32x16& p1, float alpha, float& l_reg, bf16x8& pa0, bf16x8& pa1, bf16x8& pa2, bf16x8& pa3) {
;   for (int r = 0; r < 16; ++r) p1[r] = __builtin_amdgcn_exp2f(p1[r]);
;   float ps = 0; for (int r = 0; r < 16; ++r) ps += p0[r]; for (int r = 0; r < 16; ++r) ps += p1[r];
;   { auto rr = __builtin_amdgcn_permlane32_swap(__float_as_uint(ps), __float_as_uint(ps), false, false);
;     ps = __uint_as_float(rr[0]) + __uint_as_float(rr[1]); }
;   l_reg = l_reg * alpha + ps;
;     ...
;   PK4(p0, 0, pa0); PK4(p0, 8, pa1); PK4(p1, 0, pa2); PK4(p1, 8, pa3);
;     ...
; }
; __device__ __forceinline__ void qkt(f32x16& p0, f32x16& p1, const u16* Ks, const bf16x8* qr, int r32, int hi) {
;   p0 = f32x16{}; p1 = f32x16{};
;   for (int d0 = 0; d0 < 8; ++d0) { int cb = (d0 * 16 + hi * 8) * 2;
;     bf16x8 b0 = *reinterpret_cast<const bf16x8*>((const char*)Ks + KSWZ(r32, cb));
;     bf16x8 b1 = *reinterpret_cast<const bf16x8*>((const char*)Ks + KSWZ(32 + r32, cb));
;     p0 = __builtin_amdgcn_mfma_f32_32x32x16_bf16(b0, qr[d0], p0, 0, 0, 0);
;     p1 = __builtin_amdgcn_mfma_f32_32x32x16_bf16(b1, qr[d0], p1, 0, 0, 0); }
; }
; __device__ __forceinline__ int v_st(int k, int c) { const int kk = (k & ~0xC) | ((k & 4) << 1) | ((k & 8) >> 1); return ((kk >> 3) * 4 + (c >> 5)) * 512 + ((kk & 7) * 32 + (c & 31)) * 2; }
.LBB0_864:
	ds_read_b64_tr_b16 v[216:217], v195 offset:0
	ds_read_b64_tr_b16 v[218:219], v195 offset:0x800
	ds_read_b64_tr_b16 v[220:221], v195 offset:0x1000
	ds_read_b64_tr_b16 v[222:223], v195 offset:0x1800
	ds_read_b64_tr_b16 v[224:225], v195 offset:0x2000
	ds_read_b64_tr_b16 v[226:227], v195 offset:0x2800
	ds_read_b64_tr_b16 v[228:229], v195 offset:0x3000
	ds_read_b64_tr_b16 v[230:231], v195 offset:0x3800
	s_waitcnt lgkmcnt(6)
	s_nop 0
	v_mfma_f32_32x32x16_bf16 v[0:15], v[160:163], v[216:219], v[0:15]
	ds_read_b64_tr_b16 v[216:217], v195 offset:0x200
	ds_read_b64_tr_b16 v[218:219], v195 offset:0xa00
	s_waitcnt lgkmcnt(6)
	v_mfma_f32_32x32x16_bf16 v[0:15], v[164:167], v[220:223], v[0:15]
	ds_read_b64_tr_b16 v[220:221], v195 offset:0x1200
	ds_read_b64_tr_b16 v[222:223], v195 offset:0x1a00
	s_waitcnt lgkmcnt(6)
	v_mfma_f32_32x32x16_bf16 v[0:15], v[168:171], v[224:227], v[0:15]
	ds_read_b64_tr_b16 v[224:225], v195 offset:0x2200
	ds_read_b64_tr_b16 v[226:227], v195 offset:0x2a00
	s_waitcnt lgkmcnt(6)
	v_mfma_f32_32x32x16_bf16 v[0:15], v[172:175], v[228:231], v[0:15]
	ds_read_b64_tr_b16 v[228:229], v195 offset:0x3200
	ds_read_b64_tr_b16 v[230:231], v195 offset:0x3a00
	s_waitcnt lgkmcnt(6)
	v_mfma_f32_32x32x16_bf16 v[48:63], v[160:163], v[216:219], v[48:63]
	ds_read_b64_tr_b16 v[216:217], v195 offset:0x400
	ds_read_b64_tr_b16 v[218:219], v195 offset:0xc00
	s_waitcnt lgkmcnt(6)
	v_mfma_f32_32x32x16_bf16 v[48:63], v[164:167], v[220:223], v[48:63]
	ds_read_b64_tr_b16 v[220:221], v195 offset:0x1400
	ds_read_b64_tr_b16 v[222:223], v195 offset:0x1c00
	s_waitcnt lgkmcnt(6)
	v_mfma_f32_32x32x16_bf16 v[48:63], v[168:171], v[224:227], v[48:63]
	ds_read_b64_tr_b16 v[224:225], v195 offset:0x2400
	ds_read_b64_tr_b16 v[226:227], v195 offset:0x2c00
	s_waitcnt lgkmcnt(6)
	v_mfma_f32_32x32x16_bf16 v[48:63], v[172:175], v[228:231], v[48:63]
	ds_read_b64_tr_b16 v[228:229], v195 offset:0x3400
	ds_read_b64_tr_b16 v[230:231], v195 offset:0x3c00
	s_waitcnt lgkmcnt(6)
	v_mfma_f32_32x32x16_bf16 v[32:47], v[160:163], v[216:219], v[32:47]
	ds_read_b64_tr_b16 v[216:217], v195 offset:0x600
	ds_read_b64_tr_b16 v[218:219], v195 offset:0xe00
	s_waitcnt lgkmcnt(6)
	v_mfma_f32_32x32x16_bf16 v[32:47], v[164:167], v[220:223], v[32:47]
	ds_read_b64_tr_b16 v[220:221], v195 offset:0x1600
	ds_read_b64_tr_b16 v[222:223], v195 offset:0x1e00
	s_waitcnt lgkmcnt(6)
	v_mfma_f32_32x32x16_bf16 v[32:47], v[168:171], v[224:227], v[32:47]
	ds_read_b64_tr_b16 v[224:225], v195 offset:0x2600
	ds_read_b64_tr_b16 v[226:227], v195 offset:0x2e00
	s_waitcnt lgkmcnt(6)
	v_mfma_f32_32x32x16_bf16 v[32:47], v[172:175], v[228:231], v[32:47]
	ds_read_b64_tr_b16 v[228:229], v195 offset:0x3600
	ds_read_b64_tr_b16 v[230:231], v195 offset:0x3e00
	s_waitcnt lgkmcnt(6)
	v_mfma_f32_32x32x16_bf16 v[16:31], v[160:163], v[216:219], v[16:31]
	v_max_f32_e32 v160, v81, v81
	v_max_f32_e32 v161, v80, v80
	v_max_f32_e32 v160, v161, v160
	v_max3_f32 v160, v160, v82, v83
	v_max3_f32 v160, v160, v84, v85
	v_max3_f32 v160, v160, v86, v87
	v_max3_f32 v160, v160, v88, v89
	v_max3_f32 v160, v160, v90, v91
	v_max3_f32 v160, v160, v92, v93
	s_waitcnt lgkmcnt(4)
	v_mfma_f32_32x32x16_bf16 v[16:31], v[164:167], v[220:223], v[16:31]
	v_max3_f32 v160, v160, v94, v95
	v_max3_f32 v160, v160, v64, v65
	v_max3_f32 v160, v160, v66, v67
	v_max3_f32 v160, v160, v68, v69
	v_max3_f32 v160, v160, v70, v71
	v_max3_f32 v160, v160, v72, v73
	v_max3_f32 v160, v160, v74, v75
	v_max3_f32 v160, v160, v76, v77
	s_waitcnt lgkmcnt(2)
	v_mfma_f32_32x32x16_bf16 v[16:31], v[168:171], v[224:227], v[16:31]
	v_max3_f32 v160, v160, v78, v79
	v_mov_b32_e32 v161, v160
	s_nop 1
	v_permlane32_swap_b32_e32 v160, v161
	v_max_f32_e32 v161, v161, v161
	v_max_f32_e32 v160, v160, v160
	v_max_f32_e32 v160, v160, v161
	v_sub_f32_e32 v161, v160, v213
	v_cmp_ge_f32_e32 vcc, s56, v161
	v_max_f32_e32 v161, v213, v213
	v_max_f32_e32 v161, v161, v160
	s_waitcnt lgkmcnt(0)
	v_mfma_f32_32x32x16_bf16 v[16:31], v[172:175], v[228:231], v[16:31]
	v_sub_f32_e32 v160, v213, v161
	v_mul_f32_e32 v160, 0x3e0293ee, v160
	v_exp_f32_e32 v160, v160
	s_cmp_eq_u64 vcc, exec
	s_cselect_b64 s[10:11], -1, 0
	s_barrier
	s_waitcnt vmcnt(4)
	v_cndmask_b32_e64 v160, v160, 1.0, s[10:11]
	v_cmp_gt_f32_e32 vcc, 1.0, v160
	s_cmp_eq_u64 s[24:25], 0
	s_cbranch_scc1 .Lattn_lw
	s_waitcnt vmcnt(0)

; __device__ __forceinline__ void finishSM(f32x16& p0, f32x16& p1, float alpha, float& l_reg, bf16x8& pa0, bf16x8& pa1, bf16x8& pa2, bf16x8& pa3) {
;   for (int r = 0; r < 16; ++r) p1[r] = __builtin_amdgcn_exp2f(p1[r]);
;   float ps = 0; for (int r = 0; r < 16; ++r) ps += p0[r]; for (int r = 0; r < 16; ++r) ps += p1[r];
;   { auto rr = __builtin_amdgcn_permlane32_swap(__float_as_uint(ps), __float_as_uint(ps), false, false);
;     ps = __uint_as_float(rr[0]) + __uint_as_float(rr[1]); }
;   l_reg = l_reg * alpha + ps;
;     ...
;   PK4(p0, 0, pa0); PK4(p0, 8, pa1); PK4(p1, 0, pa2); PK4(p1, 8, pa3);
;     ...
; }
; __device__ __forceinline__ void qkt(f32x16& p0, f32x16& p1, const u16* Ks, const bf16x8* qr, int r32, int hi) {
;   p0 = f32x16{}; p1 = f32x16{};
;   for (int d0 = 0; d0 < 8; ++d0) { int cb = (d0 * 16 + hi * 8) * 2;
;     bf16x8 b0 = *reinterpret_cast<const bf16x8*>((const char*)Ks + KSWZ(r32, cb));
;     bf16x8 b1 = *reinterpret_cast<const bf16x8*>((const char*)Ks + KSWZ(32 + r32, cb));
;     p0 = __builtin_amdgcn_mfma_f32_32x32x16_bf16(b0, qr[d0], p0, 0, 0, 0);
;     p1 = __builtin_amdgcn_mfma_f32_32x32x16_bf16(b1, qr[d0], p1, 0, 0, 0); }
; }
; __device__ __forceinline__ int v_st(int k, int c) { const int kk = (k & ~0xC) | ((k & 4) << 1) | ((k & 8) >> 1); return ((kk >> 3) * 4 + (c >> 5)) * 512 + ((kk & 7) * 32 + (c & 31)) * 2; }
; __device__ __forceinline__ int v_rd_base(int lane) { return ((lane & 3) << 3) | (((lane >> 2) & 3) << 6) | (((lane >> 4) & 1) << 5) | (((lane >> 5) & 1) << 8); }
; template <int OFF> __device__ __forceinline__ s16x4 tr_read(int vb) {
;   s16x4 r; asm volatile("ds_read_b64_tr_b16 %0, %1 offset:%2" : "=&v"(r) : "v"(vb), "i"(OFF) : "memory"); return r;
; }
; template <int D0> __device__ __forceinline__ void pv_one(f32x16& od, int vb, bf16x8 pa0, bf16x8 pa1, bf16x8 pa2, bf16x8 pa3) {
;   const s16x4 l0 = tr_read<v_rd_off(D0, 0, 0)>(vb), h0 = tr_read<v_rd_off(D0, 0, 1)>(vb), l1 = tr_read<v_rd_off(D0, 1, 0)>(vb), h1 = tr_read<v_rd_off(D0, 1, 1)>(vb);
;   const s16x4 l2 = tr_read<v_rd_off(D0, 2, 0)>(vb), h2 = tr_read<v_rd_off(D0, 2, 1)>(vb), l3 = tr_read<v_rd_off(D0, 3, 0)>(vb), h3 = tr_read<v_rd_off(D0, 3, 1)>(vb);
;   asm volatile("s_waitcnt lgkmcnt(0)" ::: "memory"); SBAR();
;     ...
;   od = __builtin_amdgcn_mfma_f32_32x32x16_bf16(pa0, PK(l0, h0), od, 0, 0, 0);
;   od = __builtin_amdgcn_mfma_f32_32x32x16_bf16(pa1, PK(l1, h1), od, 0, 0, 0);
.LBB0_870:
	ds_read_b128 v[64:67], v201 offset:49152
	ds_read_b128 v[68:71], v201 offset:57344
	s_waitcnt lgkmcnt(1)
	v_mfma_f32_32x32x16_bf16 v[80:95], v[64:67], v[96:99], 0
	s_waitcnt lgkmcnt(0)
	v_mfma_f32_32x32x16_bf16 v[64:79], v[68:71], v[96:99], 0
	ds_read_b128 v[96:99], v204 offset:49152
	ds_read_b128 v[128:131], v204 offset:57344
	s_waitcnt lgkmcnt(1)
	v_mfma_f32_32x32x16_bf16 v[80:95], v[96:99], v[100:103], v[80:95]
	s_waitcnt lgkmcnt(0)
	v_mfma_f32_32x32x16_bf16 v[64:79], v[128:131], v[100:103], v[64:79]
	ds_read_b128 v[96:99], v206 offset:49152
	ds_read_b128 v[100:103], v206 offset:57344
	s_waitcnt lgkmcnt(1)
	v_mfma_f32_32x32x16_bf16 v[80:95], v[96:99], v[104:107], v[80:95]
	s_waitcnt lgkmcnt(0)
	v_mfma_f32_32x32x16_bf16 v[64:79], v[100:103], v[104:107], v[64:79]
	ds_read_b128 v[96:99], v202 offset:49152
	ds_read_b128 v[100:103], v202 offset:57344
	v_exp_f32_e32 v106, v156
	v_exp_f32_e32 v107, v157
	s_waitcnt lgkmcnt(1)
	v_mfma_f32_32x32x16_bf16 v[80:95], v[96:99], v[108:111], v[80:95]
	s_waitcnt lgkmcnt(0)
	v_mfma_f32_32x32x16_bf16 v[64:79], v[100:103], v[108:111], v[64:79]
	ds_read_b128 v[96:99], v203 offset:49152
	ds_read_b128 v[100:103], v203 offset:57344
	v_exp_f32_e32 v108, v154
	v_exp_f32_e32 v109, v155
	v_exp_f32_e32 v110, v148
	v_exp_f32_e32 v111, v149
	s_waitcnt lgkmcnt(1)
	v_mfma_f32_32x32x16_bf16 v[80:95], v[96:99], v[112:115], v[80:95]
	s_waitcnt lgkmcnt(0)
	v_mfma_f32_32x32x16_bf16 v[64:79], v[100:103], v[112:115], v[64:79]
	ds_read_b128 v[96:99], v205 offset:49152
	ds_read_b128 v[100:103], v205 offset:57344
	v_exp_f32_e32 v112, v146
	v_exp_f32_e32 v113, v147
	v_exp_f32_e32 v114, v144
	v_exp_f32_e32 v115, v145
	s_waitcnt lgkmcnt(1)
	v_mfma_f32_32x32x16_bf16 v[80:95], v[96:99], v[116:119], v[80:95]
	s_waitcnt lgkmcnt(0)
	v_mfma_f32_32x32x16_bf16 v[64:79], v[100:103], v[116:119], v[64:79]
	ds_read_b128 v[96:99], v207 offset:49152
	ds_read_b128 v[100:103], v207 offset:57344
	v_exp_f32_e32 v116, v158
	v_exp_f32_e32 v117, v159
	v_exp_f32_e32 v118, v152
	v_exp_f32_e32 v119, v153
	s_waitcnt lgkmcnt(1)
	v_mfma_f32_32x32x16_bf16 v[80:95], v[96:99], v[120:123], v[80:95]
	s_waitcnt lgkmcnt(0)
	v_mfma_f32_32x32x16_bf16 v[64:79], v[100:103], v[120:123], v[64:79]
	ds_read_b128 v[96:99], v208 offset:49152
	ds_read_b128 v[100:103], v208 offset:57344
	v_exp_f32_e32 v120, v150
	v_exp_f32_e32 v121, v151
	s_waitcnt lgkmcnt(1)
	v_mfma_f32_32x32x16_bf16 v[80:95], v[96:99], v[124:127], v[80:95]
	v_add_f32_e32 v96, 0, v175
	v_add_f32_e32 v96, v216, v96
	v_add_f32_e32 v96, v161, v96
	v_add_f32_e32 v96, v213, v96
	v_add_f32_e32 v96, v162, v96
	v_add_f32_e32 v96, v174, v96
	v_add_f32_e32 v96, v163, v96
	v_add_f32_e32 v96, v173, v96
	v_add_f32_e32 v96, v170, v96
	v_add_f32_e32 v96, v172, v96
	v_add_f32_e32 v96, v169, v96
	v_add_f32_e32 v96, v171, v96
	v_add_f32_e32 v96, v166, v96
	v_add_f32_e32 v96, v168, v96
	v_add_f32_e32 v96, v165, v96
	v_add_f32_e32 v96, v167, v96
	v_add_f32_e32 v96, v106, v96
	v_add_f32_e32 v96, v107, v96
	v_add_f32_e32 v96, v108, v96
	v_add_f32_e32 v96, v109, v96
	v_add_f32_e32 v96, v110, v96
	v_add_f32_e32 v96, v111, v96
	v_add_f32_e32 v96, v112, v96
	v_add_f32_e32 v96, v113, v96
	v_add_f32_e32 v96, v114, v96
	v_add_f32_e32 v96, v115, v96
	s_waitcnt lgkmcnt(0)
	v_mfma_f32_32x32x16_bf16 v[64:79], v[100:103], v[124:127], v[64:79]
	v_add_f32_e32 v96, v116, v96
	v_add_f32_e32 v96, v117, v96
	v_add_f32_e32 v96, v118, v96
	v_add_f32_e32 v96, v119, v96
	v_add_f32_e32 v96, v120, v96
	v_add_f32_e32 v100, v121, v96
	v_mov_b32_e32 v101, v100
	v_cvt_pk_bf16_f32 v96, v175, v216
	v_cvt_pk_bf16_f32 v97, v161, v213
	v_cvt_pk_bf16_f32 v98, v162, v174
	v_cvt_pk_bf16_f32 v99, v163, v173
	s_nop 1
	v_permlane32_swap_b32_e32 v100, v101
	v_permlane32_swap_b32_e32 v96, v98
	v_permlane32_swap_b32_e32 v97, v99
	v_cvt_pk_bf16_f32 v102, v170, v172
	v_cvt_pk_bf16_f32 v103, v169, v171
	v_cvt_pk_bf16_f32 v104, v166, v168
	v_cvt_pk_bf16_f32 v105, v165, v167
	v_cvt_pk_bf16_f32 v106, v106, v107
	v_cvt_pk_bf16_f32 v107, v108, v109
	v_cvt_pk_bf16_f32 v108, v110, v111
	v_cvt_pk_bf16_f32 v109, v112, v113
	v_cvt_pk_bf16_f32 v110, v114, v115
	v_cvt_pk_bf16_f32 v111, v116, v117
	v_cvt_pk_bf16_f32 v112, v118, v119
	v_cvt_pk_bf16_f32 v113, v120, v121
	s_nop 0
	v_permlane32_swap_b32_e32 v102, v104
	v_permlane32_swap_b32_e32 v103, v105
	v_permlane32_swap_b32_e32 v106, v108
	v_permlane32_swap_b32_e32 v107, v109
	v_permlane32_swap_b32_e32 v110, v112
	v_permlane32_swap_b32_e32 v111, v113
	ds_read_b64_tr_b16 v[114:115], v196 offset:0
	ds_read_b64_tr_b16 v[116:117], v196 offset:0x800
	ds_read_b64_tr_b16 v[118:119], v196 offset:0x1000
	ds_read_b64_tr_b16 v[120:121], v196 offset:0x1800
	ds_read_b64_tr_b16 v[122:123], v196 offset:0x2000
	ds_read_b64_tr_b16 v[124:125], v196 offset:0x2800
	ds_read_b64_tr_b16 v[126:127], v196 offset:0x3000
	ds_read_b64_tr_b16 v[128:129], v196 offset:0x3800
	s_waitcnt lgkmcnt(6)
	s_nop 0
	v_mfma_f32_32x32x16_bf16 v[0:15], v[96:99], v[114:117], v[0:15]
	ds_read_b64_tr_b16 v[114:115], v196 offset:0x200
	ds_read_b64_tr_b16 v[116:117], v196 offset:0xa00
	s_waitcnt lgkmcnt(6)
	v_mfma_f32_32x32x16_bf16 v[0:15], v[102:105], v[118:121], v[0:15]
	ds_read_b64_tr_b16 v[118:119], v196 offset:0x1200
	ds_read_b64_tr_b16 v[120:121], v196 offset:0x1a00
	s_waitcnt lgkmcnt(6)
	v_mfma_f32_32x32x16_bf16 v[0:15], v[106:109], v[122:125], v[0:15]
	ds_read_b64_tr_b16 v[122:123], v196 offset:0x2200
	ds_read_b64_tr_b16 v[124:125], v196 offset:0x2a00
	s_waitcnt lgkmcnt(6)
	v_mfma_f32_32x32x16_bf16 v[0:15], v[110:113], v[126:129], v[0:15]
	ds_read_b64_tr_b16 v[126:127], v196 offset:0x3200
	ds_read_b64_tr_b16 v[128:129], v196 offset:0x3a00
	s_waitcnt lgkmcnt(6)
; __device__ __forceinline__ void partialSM(f32x16& p0, f32x16& p1, float& m_reg, float& mn, float& alpha) {
;   constexpr float C = ASCALE * 1.4426950408889634f;
;   float pmax = p0[0]; for (int r = 1; r < 16; ++r) pmax = fmaxf(pmax, p0[r]); for (int r = 0; r < 16; ++r) pmax = fmaxf(pmax, p1[r]);
;   { auto rr = __builtin_amdgcn_permlane32_swap(__float_as_uint(pmax), __float_as_uint(pmax), false, false);
;     pmax = fmaxf(__uint_as_float(rr[0]), __uint_as_float(rr[1])); }
;   if (__builtin_expect(__all(pmax - m_reg <= ATHR / ASCALE), 1)) { mn = m_reg; alpha = 1.f; }
;   else { mn = fmaxf(m_reg, pmax); alpha = __builtin_amdgcn_exp2f((m_reg - mn) * C); m_reg = mn; }
;   float mnC = -mn * C;
;   for (int r = 0; r < 16; ++r) p0[r] = fmaf(p0[r], C, mnC); for (int r = 0; r < 16; ++r) p1[r] = fmaf(p1[r], C, mnC);
;   for (int r = 0; r < 16; ++r) p0[r] = __builtin_amdgcn_exp2f(p0[r]);
; }
; __device__ __forceinline__ void finishSM(f32x16& p0, f32x16& p1, float alpha, float& l_reg, bf16x8& pa0, bf16x8& pa1, bf16x8& pa2, bf16x8& pa3) {
;   for (int r = 0; r < 16; ++r) p1[r] = __builtin_amdgcn_exp2f(p1[r]);
;   float ps = 0; for (int r = 0; r < 16; ++r) ps += p0[r]; for (int r = 0; r < 16; ++r) ps += p1[r];
;   { auto rr = __builtin_amdgcn_permlane32_swap(__float_as_uint(ps), __float_as_uint(ps), false, false);
;     ps = __uint_as_float(rr[0]) + __uint_as_float(rr[1]); }
;   l_reg = l_reg * alpha + ps;
;     ...
;   PK4(p0, 0, pa0); PK4(p0, 8, pa1); PK4(p1, 0, pa2); PK4(p1, 8, pa3);
;     ...
; }
; __device__ __forceinline__ void qkt(f32x16& p0, f32x16& p1, const u16* Ks, const bf16x8* qr, int r32, int hi) {
;   p0 = f32x16{}; p1 = f32x16{};
;   for (int d0 = 0; d0 < 8; ++d0) { int cb = (d0 * 16 + hi * 8) * 2;
;     bf16x8 b0 = *reinterpret_cast<const bf16x8*>((const char*)Ks + KSWZ(r32, cb));
;     bf16x8 b1 = *reinterpret_cast<const bf16x8*>((const char*)Ks + KSWZ(32 + r32, cb));
;     p0 = __builtin_amdgcn_mfma_f32_32x32x16_bf16(b0, qr[d0], p0, 0, 0, 0);
;     p1 = __builtin_amdgcn_mfma_f32_32x32x16_bf16(b1, qr[d0], p1, 0, 0, 0); }
; }
; __device__ __forceinline__ int v_st(int k, int c) { const int kk = (k & ~0xC) | ((k & 4) << 1) | ((k & 8) >> 1); return ((kk >> 3) * 4 + (c >> 5)) * 512 + ((kk & 7) * 32 + (c & 31)) * 2; }
	v_mfma_f32_32x32x16_bf16 v[48:63], v[96:99], v[114:117], v[48:63]
	ds_read_b64_tr_b16 v[114:115], v196 offset:0x400
	ds_read_b64_tr_b16 v[116:117], v196 offset:0xc00
	s_waitcnt lgkmcnt(6)
	v_mfma_f32_32x32x16_bf16 v[48:63], v[102:105], v[118:121], v[48:63]
	ds_read_b64_tr_b16 v[118:119], v196 offset:0x1400
	ds_read_b64_tr_b16 v[120:121], v196 offset:0x1c00
	s_waitcnt lgkmcnt(6)
	v_mfma_f32_32x32x16_bf16 v[48:63], v[106:109], v[122:125], v[48:63]
	ds_read_b64_tr_b16 v[122:123], v196 offset:0x2400
	ds_read_b64_tr_b16 v[124:125], v196 offset:0x2c00
	s_waitcnt lgkmcnt(6)
	v_mfma_f32_32x32x16_bf16 v[48:63], v[110:113], v[126:129], v[48:63]
	ds_read_b64_tr_b16 v[126:127], v196 offset:0x3400
	ds_read_b64_tr_b16 v[128:129], v196 offset:0x3c00
	s_waitcnt lgkmcnt(6)
	v_mfma_f32_32x32x16_bf16 v[32:47], v[96:99], v[114:117], v[32:47]
	ds_read_b64_tr_b16 v[114:115], v196 offset:0x600
	ds_read_b64_tr_b16 v[116:117], v196 offset:0xe00
	s_waitcnt lgkmcnt(6)
	v_mfma_f32_32x32x16_bf16 v[32:47], v[102:105], v[118:121], v[32:47]
	ds_read_b64_tr_b16 v[118:119], v196 offset:0x1600
	ds_read_b64_tr_b16 v[120:121], v196 offset:0x1e00
	s_waitcnt lgkmcnt(6)
	v_mfma_f32_32x32x16_bf16 v[32:47], v[106:109], v[122:125], v[32:47]
	ds_read_b64_tr_b16 v[122:123], v196 offset:0x2600
	ds_read_b64_tr_b16 v[124:125], v196 offset:0x2e00
	s_waitcnt lgkmcnt(6)
	v_mfma_f32_32x32x16_bf16 v[32:47], v[110:113], v[126:129], v[32:47]
	ds_read_b64_tr_b16 v[126:127], v196 offset:0x3600
	ds_read_b64_tr_b16 v[128:129], v196 offset:0x3e00
	s_waitcnt lgkmcnt(6)
	v_mfma_f32_32x32x16_bf16 v[16:31], v[96:99], v[114:117], v[16:31]
	v_max_f32_e32 v96, v81, v81
	v_max_f32_e32 v97, v80, v80
	v_max_f32_e32 v96, v97, v96
	v_max3_f32 v96, v96, v82, v83
	v_max3_f32 v96, v96, v84, v85
	v_max3_f32 v96, v96, v86, v87
	v_max3_f32 v96, v96, v88, v89
	v_max3_f32 v96, v96, v90, v91
	v_max3_f32 v96, v96, v92, v93
	s_waitcnt lgkmcnt(4)
	v_mfma_f32_32x32x16_bf16 v[16:31], v[102:105], v[118:121], v[16:31]
	v_max3_f32 v96, v96, v94, v95
	v_max3_f32 v96, v96, v64, v65
	v_max3_f32 v96, v96, v66, v67
	v_max3_f32 v96, v96, v68, v69
	v_max3_f32 v96, v96, v70, v71
	v_max3_f32 v96, v96, v72, v73
	v_max3_f32 v96, v96, v74, v75
	v_max3_f32 v96, v96, v76, v77
	s_waitcnt lgkmcnt(2)
	v_mfma_f32_32x32x16_bf16 v[16:31], v[106:109], v[122:125], v[16:31]
	v_max3_f32 v96, v96, v78, v79
	v_mov_b32_e32 v97, v96
	s_nop 1
	v_permlane32_swap_b32_e32 v96, v97
	v_max_f32_e32 v97, v97, v97
	v_max_f32_e32 v96, v96, v96
	v_max_f32_e32 v96, v96, v97
	v_sub_f32_e32 v97, v96, v164
	v_cmp_ge_f32_e32 vcc, s56, v97
	v_max_f32_e32 v97, v164, v164
	v_max_f32_e32 v97, v97, v96
	s_waitcnt lgkmcnt(0)
	v_mfma_f32_32x32x16_bf16 v[16:31], v[110:113], v[126:129], v[16:31]
	v_sub_f32_e32 v96, v164, v97
	v_mul_f32_e32 v96, 0x3e0293ee, v96
	v_exp_f32_e32 v96, v96
	s_cmp_eq_u64 vcc, exec
	s_cselect_b64 s[10:11], -1, 0
	v_cndmask_b32_e64 v96, v96, 1.0, s[10:11]
	v_cmp_gt_f32_e32 vcc, 1.0, v96
	s_barrier
	s_cbranch_vccz .LBB0_874
	s_and_saveexec_b64 s[4:5], s[8:9]
	ds_write_b32 v193, v96 offset:128
	s_or_b64 exec, exec, s[4:5]
	s_waitcnt lgkmcnt(0)
	v_add_u32_e32 v98, v179, v176
	ds_read_b128 v[102:105], v98 offset:224
	ds_read_b128 v[106:109], v98 offset:192
	ds_read_b128 v[110:113], v98 offset:160
	ds_read_b128 v[114:117], v98 offset:128
	s_waitcnt lgkmcnt(3)
	v_pk_mul_f32 v[12:13], v[12:13], v[102:103]
	s_waitcnt lgkmcnt(2)
	v_pk_mul_f32 v[8:9], v[8:9], v[106:107]
	s_waitcnt lgkmcnt(1)
	v_pk_mul_f32 v[4:5], v[4:5], v[110:111]
	v_pk_mul_f32 v[14:15], v[14:15], v[104:105]
	v_pk_mul_f32 v[10:11], v[10:11], v[108:109]
	v_pk_mul_f32 v[6:7], v[6:7], v[112:113]
	s_waitcnt lgkmcnt(0)
	v_pk_mul_f32 v[2:3], v[2:3], v[116:117]
	v_pk_mul_f32 v[0:1], v[0:1], v[114:115]
	v_pk_mul_f32 v[60:61], v[60:61], v[102:103]
	v_pk_mul_f32 v[56:57], v[56:57], v[106:107]
	v_pk_mul_f32 v[52:53], v[52:53], v[110:111]
	v_pk_mul_f32 v[62:63], v[62:63], v[104:105]
	v_pk_mul_f32 v[58:59], v[58:59], v[108:109]
	v_pk_mul_f32 v[54:55], v[54:55], v[112:113]
	v_pk_mul_f32 v[50:51], v[50:51], v[116:117]
	v_pk_mul_f32 v[48:49], v[48:49], v[114:115]
	v_pk_mul_f32 v[44:45], v[44:45], v[102:103]
	v_pk_mul_f32 v[40:41], v[40:41], v[106:107]
	v_pk_mul_f32 v[36:37], v[36:37], v[110:111]
	v_pk_mul_f32 v[46:47], v[46:47], v[104:105]
	v_pk_mul_f32 v[42:43], v[42:43], v[108:109]
	v_pk_mul_f32 v[38:39], v[38:39], v[112:113]
	v_pk_mul_f32 v[34:35], v[34:35], v[116:117]
	v_pk_mul_f32 v[32:33], v[32:33], v[114:115]
	v_pk_mul_f32 v[28:29], v[28:29], v[102:103]
	v_pk_mul_f32 v[24:25], v[24:25], v[106:107]
	v_pk_mul_f32 v[20:21], v[20:21], v[110:111]
	v_pk_mul_f32 v[30:31], v[30:31], v[104:105]
	v_pk_mul_f32 v[26:27], v[26:27], v[108:109]
	v_pk_mul_f32 v[22:23], v[22:23], v[112:113]
	v_pk_mul_f32 v[18:19], v[18:19], v[116:117]
	v_pk_mul_f32 v[16:17], v[16:17], v[114:115]
; __device__ __forceinline__ void partialSM(f32x16& p0, f32x16& p1, float& m_reg, float& mn, float& alpha) {
;     ...
;   float mnC = -mn * C;
;   for (int r = 0; r < 16; ++r) p0[r] = fmaf(p0[r], C, mnC); for (int r = 0; r < 16; ++r) p1[r] = fmaf(p1[r], C, mnC);
;   for (int r = 0; r < 16; ++r) p0[r] = __builtin_amdgcn_exp2f(p0[r]);
; }
; __device__ __forceinline__ void finishSM(f32x16& p0, f32x16& p1, float alpha, float& l_reg, bf16x8& pa0, bf16x8& pa1, bf16x8& pa2, bf16x8& pa3) {
;   for (int r = 0; r < 16; ++r) p1[r] = __builtin_amdgcn_exp2f(p1[r]);
;   float ps = 0; for (int r = 0; r < 16; ++r) ps += p0[r]; for (int r = 0; r < 16; ++r) ps += p1[r];
;   { auto rr = __builtin_amdgcn_permlane32_swap(__float_as_uint(ps), __float_as_uint(ps), false, false);
;     ps = __uint_as_float(rr[0]) + __uint_as_float(rr[1]); }
;   l_reg = l_reg * alpha + ps;
;     ...
;   PK4(p0, 0, pa0); PK4(p0, 8, pa1); PK4(p1, 0, pa2); PK4(p1, 8, pa3);
;     ...
; }
; __device__ __forceinline__ void qkt(f32x16& p0, f32x16& p1, const u16* Ks, const bf16x8* qr, int r32, int hi) {
;   p0 = f32x16{}; p1 = f32x16{};
;   for (int d0 = 0; d0 < 8; ++d0) { int cb = (d0 * 16 + hi * 8) * 2;
;     bf16x8 b0 = *reinterpret_cast<const bf16x8*>((const char*)Ks + KSWZ(r32, cb));
;     bf16x8 b1 = *reinterpret_cast<const bf16x8*>((const char*)Ks + KSWZ(32 + r32, cb));
;     p0 = __builtin_amdgcn_mfma_f32_32x32x16_bf16(b0, qr[d0], p0, 0, 0, 0);
;     p1 = __builtin_amdgcn_mfma_f32_32x32x16_bf16(b1, qr[d0], p1, 0, 0, 0); }
; }
; __device__ __forceinline__ int v_st(int k, int c) { const int kk = (k & ~0xC) | ((k & 4) << 1) | ((k & 8) >> 1); return ((kk >> 3) * 4 + (c >> 5)) * 512 + ((kk & 7) * 32 + (c & 31)) * 2; }
; __device__ __forceinline__ int v_rd_base(int lane) { return ((lane & 3) << 3) | (((lane >> 2) & 3) << 6) | (((lane >> 4) & 1) << 5) | (((lane >> 5) & 1) << 8); }
; template <int OFF> __device__ __forceinline__ s16x4 tr_read(int vb) {
;   s16x4 r; asm volatile("ds_read_b64_tr_b16 %0, %1 offset:%2" : "=&v"(r) : "v"(vb), "i"(OFF) : "memory"); return r;
; }
; template <int D0> __device__ __forceinline__ void pv_one(f32x16& od, int vb, bf16x8 pa0, bf16x8 pa1, bf16x8 pa2, bf16x8 pa3) {
;   const s16x4 l0 = tr_read<v_rd_off(D0, 0, 0)>(vb), h0 = tr_read<v_rd_off(D0, 0, 1)>(vb), l1 = tr_read<v_rd_off(D0, 1, 0)>(vb), h1 = tr_read<v_rd_off(D0, 1, 1)>(vb);
.LBB0_874:
	v_cndmask_b32_e64 v97, v97, v164, s[10:11]
	v_mul_f32_e32 v97, 0xbe0293ee, v97
	v_fmamk_f32 v80, v80, 0x3e0293ee, v97
	v_fmamk_f32 v81, v81, 0x3e0293ee, v97
	v_fmamk_f32 v98, v82, 0x3e0293ee, v97
	v_exp_f32_e32 v82, v80
	v_fmamk_f32 v99, v84, 0x3e0293ee, v97
	v_exp_f32_e32 v84, v81
	v_fmamk_f32 v83, v83, 0x3e0293ee, v97
	v_exp_f32_e32 v80, v98
	v_fmamk_f32 v64, v64, 0x3e0293ee, v97
	v_exp_f32_e32 v83, v83
	v_fmamk_f32 v102, v85, 0x3e0293ee, v97
	v_fmamk_f32 v111, v94, 0x3e0293ee, v97
	v_fmamk_f32 v94, v75, 0x3e0293ee, v97
	v_exp_f32_e32 v75, v99
	v_exp_f32_e32 v98, v64
	v_add_f32_e32 v64, 0, v82
	v_fmamk_f32 v103, v86, 0x3e0293ee, v97
	v_exp_f32_e32 v81, v102
	v_add_f32_e32 v64, v84, v64
	v_fmamk_f32 v104, v87, 0x3e0293ee, v97
	v_fmamk_f32 v110, v93, 0x3e0293ee, v97
	v_fmamk_f32 v93, v74, 0x3e0293ee, v97
	v_exp_f32_e32 v74, v103
	v_add_f32_e32 v64, v80, v64
	v_fmamk_f32 v105, v88, 0x3e0293ee, v97
	v_fmamk_f32 v112, v95, 0x3e0293ee, v97
	v_fmamk_f32 v95, v76, 0x3e0293ee, v97
	v_exp_f32_e32 v76, v104
	v_add_f32_e32 v64, v83, v64
	v_fmamk_f32 v106, v89, 0x3e0293ee, v97
	v_fmamk_f32 v107, v90, 0x3e0293ee, v97
	v_fmamk_f32 v90, v71, 0x3e0293ee, v97
	v_exp_f32_e32 v71, v105
	v_add_f32_e32 v64, v75, v64
	v_fmamk_f32 v109, v92, 0x3e0293ee, v97
	v_fmamk_f32 v92, v73, 0x3e0293ee, v97
	v_exp_f32_e32 v73, v106
	v_add_f32_e32 v64, v81, v64
	v_fmamk_f32 v108, v91, 0x3e0293ee, v97
	v_fmamk_f32 v88, v69, 0x3e0293ee, v97
	v_exp_f32_e32 v69, v107
	v_add_f32_e32 v64, v74, v64
	v_fmamk_f32 v91, v72, 0x3e0293ee, v97
	v_exp_f32_e32 v72, v108
	v_add_f32_e32 v64, v76, v64
	v_fmamk_f32 v86, v67, 0x3e0293ee, v97
	v_exp_f32_e32 v67, v109
	v_add_f32_e32 v64, v71, v64
	v_fmamk_f32 v89, v70, 0x3e0293ee, v97
	v_exp_f32_e32 v70, v110
	v_add_f32_e32 v64, v73, v64
	v_fmamk_f32 v85, v66, 0x3e0293ee, v97
	v_exp_f32_e32 v66, v111
	v_add_f32_e32 v64, v69, v64
	v_fmamk_f32 v87, v68, 0x3e0293ee, v97
	v_exp_f32_e32 v68, v112
	v_add_f32_e32 v64, v72, v64
	v_fmamk_f32 v65, v65, 0x3e0293ee, v97
	v_add_f32_e32 v64, v67, v64
	v_exp_f32_e32 v99, v65
	v_add_f32_e32 v64, v70, v64
	v_exp_f32_e32 v85, v85
	v_add_f32_e32 v64, v66, v64
	v_exp_f32_e32 v86, v86
	v_add_f32_e32 v64, v68, v64
	v_exp_f32_e32 v87, v87
	v_add_f32_e32 v64, v98, v64
	v_exp_f32_e32 v88, v88
	v_add_f32_e32 v64, v99, v64
	v_exp_f32_e32 v89, v89
	v_add_f32_e32 v64, v85, v64
	v_exp_f32_e32 v90, v90
	v_add_f32_e32 v64, v86, v64
	v_exp_f32_e32 v91, v91
	v_add_f32_e32 v64, v87, v64
	v_exp_f32_e32 v92, v92
	v_add_f32_e32 v64, v88, v64
	v_exp_f32_e32 v93, v93
	v_add_f32_e32 v64, v89, v64
	v_exp_f32_e32 v94, v94
	v_add_f32_e32 v64, v90, v64
	v_fmamk_f32 v77, v77, 0x3e0293ee, v97
	v_exp_f32_e32 v95, v95
	v_add_f32_e32 v64, v91, v64
	v_fmamk_f32 v78, v78, 0x3e0293ee, v97
	v_exp_f32_e32 v102, v77
	v_add_f32_e32 v64, v92, v64
	v_fmac_f32_e32 v97, 0x3e0293ee, v79
	v_exp_f32_e32 v103, v78
	v_add_f32_e32 v64, v93, v64
	v_exp_f32_e32 v97, v97
	v_add_f32_e32 v64, v94, v64
	v_add_f32_e32 v64, v95, v64
	v_add_f32_e32 v64, v102, v64
	v_add_f32_e32 v64, v103, v64
	v_add_f32_e32 v64, v97, v64
	v_mov_b32_e32 v65, v64
	s_nop 1
	v_permlane32_swap_b32_e32 v64, v65
	v_cvt_pk_bf16_f32 v78, v82, v84
	v_cvt_pk_bf16_f32 v79, v80, v83
	v_cvt_pk_bf16_f32 v80, v75, v81
	v_cvt_pk_bf16_f32 v81, v74, v76
	v_cvt_pk_bf16_f32 v74, v71, v73
	v_cvt_pk_bf16_f32 v75, v69, v72
	v_cvt_pk_bf16_f32 v76, v67, v70
	v_cvt_pk_bf16_f32 v77, v66, v68
	v_cvt_pk_bf16_f32 v66, v98, v99
	v_cvt_pk_bf16_f32 v67, v85, v86
	v_cvt_pk_bf16_f32 v68, v87, v88
	v_cvt_pk_bf16_f32 v69, v89, v90
	v_cvt_pk_bf16_f32 v70, v91, v92
	v_cvt_pk_bf16_f32 v71, v93, v94
	v_cvt_pk_bf16_f32 v72, v95, v102
	v_cvt_pk_bf16_f32 v73, v103, v97
	s_nop 0
	v_permlane32_swap_b32_e32 v78, v80
	v_permlane32_swap_b32_e32 v79, v81
	v_permlane32_swap_b32_e32 v74, v76
	v_permlane32_swap_b32_e32 v75, v77
	v_permlane32_swap_b32_e32 v66, v68
	v_permlane32_swap_b32_e32 v67, v69
	v_permlane32_swap_b32_e32 v70, v72
	v_permlane32_swap_b32_e32 v71, v73
	ds_read_b64_tr_b16 v[82:83], v195 offset:0
	ds_read_b64_tr_b16 v[84:85], v195 offset:0x800
	ds_read_b64_tr_b16 v[86:87], v195 offset:0x1000
	ds_read_b64_tr_b16 v[88:89], v195 offset:0x1800
	ds_read_b64_tr_b16 v[90:91], v195 offset:0x2000
	ds_read_b64_tr_b16 v[92:93], v195 offset:0x2800
	ds_read_b64_tr_b16 v[102:103], v195 offset:0x3000
	ds_read_b64_tr_b16 v[104:105], v195 offset:0x3800
	s_waitcnt lgkmcnt(6)
	s_nop 0
	v_mfma_f32_32x32x16_bf16 v[0:15], v[78:81], v[82:85], v[0:15]
	ds_read_b64_tr_b16 v[82:83], v195 offset:0x200
	ds_read_b64_tr_b16 v[84:85], v195 offset:0xa00
	s_waitcnt lgkmcnt(6)
	v_mfma_f32_32x32x16_bf16 v[0:15], v[74:77], v[86:89], v[0:15]
	ds_read_b64_tr_b16 v[86:87], v195 offset:0x1200
	ds_read_b64_tr_b16 v[88:89], v195 offset:0x1a00
	s_waitcnt lgkmcnt(6)
	v_mfma_f32_32x32x16_bf16 v[0:15], v[66:69], v[90:93], v[0:15]
	ds_read_b64_tr_b16 v[90:91], v195 offset:0x2200
	ds_read_b64_tr_b16 v[92:93], v195 offset:0x2a00
	s_waitcnt lgkmcnt(6)
	v_mfma_f32_32x32x16_bf16 v[0:15], v[70:73], v[102:105], v[0:15]
	ds_read_b64_tr_b16 v[102:103], v195 offset:0x3200
	ds_read_b64_tr_b16 v[104:105], v195 offset:0x3a00
	s_waitcnt lgkmcnt(6)
	v_mfma_f32_32x32x16_bf16 v[48:63], v[78:81], v[82:85], v[48:63]
	ds_read_b64_tr_b16 v[82:83], v195 offset:0x400
	ds_read_b64_tr_b16 v[84:85], v195 offset:0xc00
	s_waitcnt lgkmcnt(6)
	v_mfma_f32_32x32x16_bf16 v[48:63], v[74:77], v[86:89], v[48:63]
	ds_read_b64_tr_b16 v[86:87], v195 offset:0x1400
	ds_read_b64_tr_b16 v[88:89], v195 offset:0x1c00
	s_waitcnt lgkmcnt(6)
	v_mfma_f32_32x32x16_bf16 v[48:63], v[66:69], v[90:93], v[48:63]
	ds_read_b64_tr_b16 v[90:91], v195 offset:0x2400
	ds_read_b64_tr_b16 v[92:93], v195 offset:0x2c00
	s_waitcnt lgkmcnt(6)
	v_mfma_f32_32x32x16_bf16 v[48:63], v[70:73], v[102:105], v[48:63]
	ds_read_b64_tr_b16 v[102:103], v195 offset:0x3400
	ds_read_b64_tr_b16 v[104:105], v195 offset:0x3c00
	s_waitcnt lgkmcnt(6)
	v_mfma_f32_32x32x16_bf16 v[32:47], v[78:81], v[82:85], v[32:47]
	ds_read_b64_tr_b16 v[82:83], v195 offset:0x600
	ds_read_b64_tr_b16 v[84:85], v195 offset:0xe00
	s_waitcnt lgkmcnt(6)
	v_mfma_f32_32x32x16_bf16 v[32:47], v[74:77], v[86:89], v[32:47]
	ds_read_b64_tr_b16 v[86:87], v195 offset:0x1600
	ds_read_b64_tr_b16 v[88:89], v195 offset:0x1e00
	s_waitcnt lgkmcnt(6)
	v_mfma_f32_32x32x16_bf16 v[32:47], v[66:69], v[90:93], v[32:47]
	ds_read_b64_tr_b16 v[90:91], v195 offset:0x2600
	ds_read_b64_tr_b16 v[92:93], v195 offset:0x2e00
	s_waitcnt lgkmcnt(6)
	v_mfma_f32_32x32x16_bf16 v[32:47], v[70:73], v[102:105], v[32:47]
	ds_read_b64_tr_b16 v[102:103], v195 offset:0x3600
	ds_read_b64_tr_b16 v[104:105], v195 offset:0x3e00
	s_waitcnt lgkmcnt(6)
	v_mfma_f32_32x32x16_bf16 v[16:31], v[78:81], v[82:85], v[16:31]
	s_waitcnt lgkmcnt(4)
	v_mfma_f32_32x32x16_bf16 v[16:31], v[74:77], v[86:89], v[16:31]
	s_waitcnt lgkmcnt(2)
	v_mfma_f32_32x32x16_bf16 v[16:31], v[66:69], v[90:93], v[16:31]
	s_waitcnt lgkmcnt(0)
	v_mfma_f32_32x32x16_bf16 v[16:31], v[70:73], v[102:105], v[16:31]
	s_and_saveexec_b64 s[4:5], s[8:9]
	s_cbranch_execz .LBB0_856
; __device__ __forceinline__ void finishSM(f32x16& p0, f32x16& p1, float alpha, float& l_reg, bf16x8& pa0, bf16x8& pa1, bf16x8& pa2, bf16x8& pa3) {
;     ...
;   { auto rr = __builtin_amdgcn_permlane32_swap(__float_as_uint(ps), __float_as_uint(ps), false, false);
;     ps = __uint_as_float(rr[0]) + __uint_as_float(rr[1]); }
;   l_reg = l_reg * alpha + ps;
; __device__ __forceinline__ void attn_dense_body(const u16* __restrict__ Qb, const u16* __restrict__ Kh, const u16* __restrict__ Vh,
;                                                 u16* __restrict__ Ob, int seq, char* lds, const float* __restrict__ qgain, const float* __restrict__ ropetab, int t0) {
;     ...
;   if (hi == 0) li_l[r32] = l_reg; asm volatile("s_waitcnt lgkmcnt(0)" ::: "memory");
	v_add_f32_e32 v66, v100, v101
	v_fmac_f32_e32 v66, v194, v160
	v_add_f32_e32 v64, v64, v65
	v_fmac_f32_e32 v64, v66, v96
	ds_write_b32 v193, v64
	s_branch .LBB0_856
